# v42: SwiGLU epilogues (P1/P9) read all four rstd pairs from LDS at the top (was 4 read+immediate-wait round trips)
# baseline (speedup 1.0000x reference)
; #define LAS __attribute__((address_space(3)))
; __device__ __forceinline__ float siluf_(float x) { return x * sigmoidf_(x); }
; __device__ __forceinline__ u32x4 pack8(const f32x4 a, const f32x4 b) { u32x4 w; w.x = cvtpk(a[0], a[1]); w.y = cvtpk(a[2], a[3]); w.z = cvtpk(b[0], b[1]); w.w = cvtpk(b[2], b[3]); return w; }
;     __device__ __forceinline__ void operator()(const Acc& acc, const Unit& u, int wr, int wc, int fr, int fq) const {
;         const int col0 = u.pn * 128 + wc * 32 + 8 * fq;
;         const LAS float* rt = rtab + u.idx * 256 + wr * 64 + fr;
; #pragma unroll
;         for (int ai = 0; ai < 2; ++ai)
; #pragma unroll
;             for (int m = 0; m < 4; ++m) {
;                 const int row = u.pm * BM + ai * HALF + wr * 64 + m * 16 + fr; const float r = rt[ai * HALF + m * 16];
;                 f32x4 h0, h1;
; #pragma unroll
;                 for (int e = 0; e < 4; ++e) { h0[e] = siluf_(acc[ai][0][m][0][e] * r) * (acc[ai][1][m][0][e] * r); h1[e] = siluf_(acc[ai][0][m][1][e] * r) * (acc[ai][1][m][1][e] * r); }
;                 *(u32x4*)(H + (size_t)row * FF + col0) = pack8(h0, h1);
;             }
.LBB0_587:
	v_lshl_add_u32 v156, s78, 10, v148
	ds_read2_b32 v[158:159], v156 offset1:16
	ds_read2_b32 v[232:233], v156 offset0:32 offset1:48
	ds_read2_b32 v[234:235], v156 offset0:128 offset1:144
	ds_read2_b32 v[236:237], v156 offset0:160 offset1:176
	v_lshl_or_b32 v160, s79, 7, v152
	s_lshl_b32 s19, s30, 8
	v_ashrrev_i32_e32 v161, 31, v160
	s_andn2_b64 vcc, exec, s[0:1]
	s_waitcnt lgkmcnt(0)
	v_pk_mul_f32 v[126:127], v[126:127], v[158:159] op_sel_hi:[1,0]
	v_pk_mul_f32 v[122:123], v[122:123], v[158:159] op_sel_hi:[1,0]
	v_mul_f32_e32 v157, 0xbfb8aa3b, v126
	v_mul_f32_e32 v162, 0xbfb8aa3b, v127
	v_exp_f32_e32 v157, v157
	v_exp_f32_e32 v162, v162
	v_mul_f32_e32 v163, 0xbfb8aa3b, v122
	v_pk_mul_f32 v[118:119], v[118:119], v[158:159] op_sel_hi:[1,0]
	v_add_f32_e32 v157, 1.0, v157
	v_add_f32_e32 v164, 1.0, v162
	v_rcp_f32_e32 v162, v157
	v_exp_f32_e32 v157, v163
	v_mul_f32_e32 v163, 0xbfb8aa3b, v123
	v_exp_f32_e32 v165, v163
	v_rcp_f32_e32 v163, v164
	v_add_f32_e32 v157, 1.0, v157
	v_rcp_f32_e32 v164, v157
	v_add_f32_e32 v157, 1.0, v165
	v_rcp_f32_e32 v165, v157
	v_pk_mul_f32 v[126:127], v[126:127], v[162:163]
	v_pk_mul_f32 v[114:115], v[114:115], v[158:159] op_sel_hi:[1,0]
	v_pk_mul_f32 v[126:127], v[118:119], v[126:127]
	v_pk_mul_f32 v[118:119], v[122:123], v[164:165]
	v_pk_mul_f32 v[122:123], v[128:129], v[158:159] op_sel_hi:[1,0]
	v_pk_mul_f32 v[124:125], v[124:125], v[158:159] op_sel_hi:[1,0]
	v_mul_f32_e32 v128, 0xbfb8aa3b, v122
	v_mul_f32_e32 v129, 0xbfb8aa3b, v123
	v_exp_f32_e32 v128, v128
	v_exp_f32_e32 v129, v129
	v_pk_mul_f32 v[114:115], v[114:115], v[118:119]
	v_pk_mul_f32 v[120:121], v[120:121], v[158:159] op_sel_hi:[1,0]
	v_add_f32_e32 v118, 1.0, v128
	v_add_f32_e32 v119, 1.0, v129
	v_mul_f32_e32 v128, 0xbfb8aa3b, v124
	v_mul_f32_e32 v129, 0xbfb8aa3b, v125
	v_exp_f32_e32 v128, v128
	v_exp_f32_e32 v129, v129
	v_rcp_f32_e32 v118, v118
	v_rcp_f32_e32 v119, v119
	v_add_f32_e32 v128, 1.0, v128
	v_add_f32_e32 v129, 1.0, v129
	v_rcp_f32_e32 v128, v128
	v_rcp_f32_e32 v129, v129
	v_pk_mul_f32 v[118:119], v[122:123], v[118:119]
	v_pk_mul_f32 v[116:117], v[116:117], v[158:159] op_sel_hi:[1,0]
	v_pk_mul_f32 v[122:123], v[120:121], v[118:119]
	v_cvt_pk_bf16_f32 v120, v126, v127
	v_mov_b32_e32 v126, v159
	v_pk_mul_f32 v[110:111], v[110:111], v[126:127] op_sel_hi:[1,0]
	v_pk_mul_f32 v[118:119], v[124:125], v[128:129]
	v_mul_f32_e32 v127, 0xbfb8aa3b, v111
	v_pk_mul_f32 v[116:117], v[116:117], v[118:119]
	v_mul_f32_e32 v119, 0xbfb8aa3b, v110
	v_exp_f32_e32 v127, v127
	v_exp_f32_e32 v119, v119
	v_add_u32_e32 v118, s19, v146
	v_cvt_pk_bf16_f32 v121, v122, v123
	v_cvt_pk_bf16_f32 v122, v114, v115
	v_mov_b64_e32 v[114:115], s[80:81]
	v_cvt_pk_bf16_f32 v123, v116, v117
	v_mad_i64_i32 v[124:125], s[34:35], v118, s74, v[114:115]
	v_lshlrev_b64 v[116:117], 1, v[160:161]
	v_lshl_add_u64 v[124:125], v[124:125], 0, v[116:117]
	v_pk_mul_f32 v[106:107], v[106:107], v[126:127] op_sel_hi:[1,0]
	global_store_dwordx4 v[124:125], v[120:123], off
	v_add_f32_e32 v119, 1.0, v119
	v_pk_mul_f32 v[102:103], v[102:103], v[126:127] op_sel_hi:[1,0]
	v_mul_f32_e32 v121, 0xbfb8aa3b, v106
	v_rcp_f32_e32 v120, v119
	v_add_f32_e32 v119, 1.0, v127
	v_exp_f32_e32 v122, v121
	v_mul_f32_e32 v121, 0xbfb8aa3b, v107
	v_exp_f32_e32 v123, v121
	v_rcp_f32_e32 v121, v119
	v_add_f32_e32 v119, 1.0, v122
	v_rcp_f32_e32 v122, v119
	v_add_f32_e32 v119, 1.0, v123
	v_pk_mul_f32 v[110:111], v[110:111], v[120:121]
	v_rcp_f32_e32 v123, v119
	v_pk_mul_f32 v[102:103], v[102:103], v[110:111]
	v_pk_mul_f32 v[110:111], v[112:113], v[126:127] op_sel_hi:[1,0]
	v_pk_mul_f32 v[98:99], v[98:99], v[126:127] op_sel_hi:[1,0]
	v_mul_f32_e32 v112, 0xbfb8aa3b, v110
	v_mul_f32_e32 v113, 0xbfb8aa3b, v111
	v_exp_f32_e32 v112, v112
	v_exp_f32_e32 v113, v113
	v_pk_mul_f32 v[106:107], v[106:107], v[122:123]
	v_pk_mul_f32 v[108:109], v[108:109], v[126:127] op_sel_hi:[1,0]
	v_pk_mul_f32 v[106:107], v[98:99], v[106:107]
	v_add_f32_e32 v98, 1.0, v112
	v_add_f32_e32 v99, 1.0, v113
	v_mul_f32_e32 v112, 0xbfb8aa3b, v108
	v_mul_f32_e32 v113, 0xbfb8aa3b, v109
	v_exp_f32_e32 v112, v112
	v_exp_f32_e32 v113, v113
	v_rcp_f32_e32 v98, v98
	v_rcp_f32_e32 v99, v99
	v_add_f32_e32 v112, 1.0, v112
	v_add_f32_e32 v113, 1.0, v113
	v_rcp_f32_e32 v112, v112
	v_rcp_f32_e32 v113, v113
	v_pk_mul_f32 v[98:99], v[110:111], v[98:99]
	v_pk_mul_f32 v[104:105], v[104:105], v[126:127] op_sel_hi:[1,0]
	v_pk_mul_f32 v[100:101], v[100:101], v[126:127] op_sel_hi:[1,0]
	v_pk_mul_f32 v[104:105], v[104:105], v[98:99]
	v_pk_mul_f32 v[98:99], v[108:109], v[112:113]
	v_add_u32_e32 v110, s19, v149
	v_pk_mul_f32 v[108:109], v[100:101], v[98:99]
	v_cvt_pk_bf16_f32 v98, v102, v103
	v_cvt_pk_bf16_f32 v100, v106, v107
	v_cvt_pk_bf16_f32 v99, v104, v105
	v_mad_i64_i32 v[104:105], s[34:35], v110, s74, v[114:115]
	s_waitcnt lgkmcnt(0)
; __device__ __forceinline__ float siluf_(float x) { return x * sigmoidf_(x); }
; __device__ __forceinline__ u32x4 pack8(const f32x4 a, const f32x4 b) { u32x4 w; w.x = cvtpk(a[0], a[1]); w.y = cvtpk(a[2], a[3]); w.z = cvtpk(b[0], b[1]); w.w = cvtpk(b[2], b[3]); return w; }
;     __device__ __forceinline__ void operator()(const Acc& acc, const Unit& u, int wr, int wc, int fr, int fq) const {
;     ...
;                 const int row = u.pm * BM + ai * HALF + wr * 64 + m * 16 + fr; const float r = rt[ai * HALF + m * 16];
;                 f32x4 h0, h1;
; #pragma unroll
;                 for (int e = 0; e < 4; ++e) { h0[e] = siluf_(acc[ai][0][m][0][e] * r) * (acc[ai][1][m][0][e] * r); h1[e] = siluf_(acc[ai][0][m][1][e] * r) * (acc[ai][1][m][1][e] * r); }
;                 *(u32x4*)(H + (size_t)row * FF + col0) = pack8(h0, h1);
	v_pk_mul_f32 v[94:95], v[94:95], v[232:233] op_sel_hi:[1,0]
	v_cvt_pk_bf16_f32 v101, v108, v109
	v_mul_f32_e32 v106, 0xbfb8aa3b, v94
	v_mul_f32_e32 v107, 0xbfb8aa3b, v95
	v_exp_f32_e32 v106, v106
	v_exp_f32_e32 v107, v107
	v_lshl_add_u64 v[104:105], v[104:105], 0, v[116:117]
	global_store_dwordx4 v[104:105], v[98:101], off
	v_pk_mul_f32 v[90:91], v[90:91], v[232:233] op_sel_hi:[1,0]
	v_pk_mul_f32 v[86:87], v[86:87], v[232:233] op_sel_hi:[1,0]
	v_add_f32_e32 v98, 1.0, v106
	v_add_f32_e32 v99, 1.0, v107
	v_rcp_f32_e32 v98, v98
	v_mul_f32_e32 v100, 0xbfb8aa3b, v90
	v_mul_f32_e32 v101, 0xbfb8aa3b, v91
	v_rcp_f32_e32 v99, v99
	v_exp_f32_e32 v100, v100
	v_exp_f32_e32 v101, v101
	v_pk_mul_f32 v[82:83], v[82:83], v[232:233] op_sel_hi:[1,0]
	v_pk_mul_f32 v[94:95], v[94:95], v[98:99]
	v_add_f32_e32 v100, 1.0, v100
	v_add_f32_e32 v101, 1.0, v101
	v_pk_mul_f32 v[86:87], v[86:87], v[94:95]
	v_pk_mul_f32 v[94:95], v[96:97], v[232:233] op_sel_hi:[1,0]
	v_rcp_f32_e32 v100, v100
	v_rcp_f32_e32 v101, v101
	v_mul_f32_e32 v96, 0xbfb8aa3b, v94
	v_mul_f32_e32 v97, 0xbfb8aa3b, v95
	v_exp_f32_e32 v96, v96
	v_exp_f32_e32 v97, v97
	v_pk_mul_f32 v[90:91], v[90:91], v[100:101]
	v_pk_mul_f32 v[92:93], v[92:93], v[232:233] op_sel_hi:[1,0]
	v_pk_mul_f32 v[90:91], v[82:83], v[90:91]
	v_add_f32_e32 v82, 1.0, v96
	v_add_f32_e32 v83, 1.0, v97
	v_mul_f32_e32 v96, 0xbfb8aa3b, v92
	v_mul_f32_e32 v97, 0xbfb8aa3b, v93
	v_exp_f32_e32 v96, v96
	v_exp_f32_e32 v97, v97
	v_rcp_f32_e32 v82, v82
	v_rcp_f32_e32 v83, v83
	v_add_f32_e32 v96, 1.0, v96
	v_add_f32_e32 v97, 1.0, v97
	v_rcp_f32_e32 v96, v96
	v_rcp_f32_e32 v97, v97
	v_pk_mul_f32 v[82:83], v[94:95], v[82:83]
	v_pk_mul_f32 v[88:89], v[88:89], v[232:233] op_sel_hi:[1,0]
	v_pk_mul_f32 v[84:85], v[84:85], v[232:233] op_sel_hi:[1,0]
	v_pk_mul_f32 v[88:89], v[88:89], v[82:83]
	v_pk_mul_f32 v[82:83], v[92:93], v[96:97]
	v_add_u32_e32 v94, s19, v150
	v_pk_mul_f32 v[92:93], v[84:85], v[82:83]
	v_cvt_pk_bf16_f32 v83, v88, v89
	v_mov_b32_e32 v88, v233
	v_pk_mul_f32 v[78:79], v[78:79], v[88:89] op_sel_hi:[1,0]
	v_cvt_pk_bf16_f32 v84, v90, v91
	v_mul_f32_e32 v89, 0xbfb8aa3b, v78
	v_mul_f32_e32 v90, 0xbfb8aa3b, v79
	v_exp_f32_e32 v89, v89
	v_exp_f32_e32 v90, v90
	v_cvt_pk_bf16_f32 v82, v86, v87
	v_mad_i64_i32 v[86:87], s[34:35], v94, s74, v[114:115]
	v_cvt_pk_bf16_f32 v85, v92, v93
	v_lshl_add_u64 v[86:87], v[86:87], 0, v[116:117]
	global_store_dwordx4 v[86:87], v[82:85], off
	v_pk_mul_f32 v[74:75], v[74:75], v[88:89] op_sel_hi:[1,0]
	v_pk_mul_f32 v[70:71], v[70:71], v[88:89] op_sel_hi:[1,0]
	v_add_f32_e32 v82, 1.0, v89
	v_add_f32_e32 v83, 1.0, v90
	v_rcp_f32_e32 v82, v82
	v_mul_f32_e32 v84, 0xbfb8aa3b, v74
	v_mul_f32_e32 v85, 0xbfb8aa3b, v75
	v_rcp_f32_e32 v83, v83
	v_exp_f32_e32 v84, v84
	v_exp_f32_e32 v85, v85
	v_pk_mul_f32 v[66:67], v[66:67], v[88:89] op_sel_hi:[1,0]
	v_pk_mul_f32 v[78:79], v[78:79], v[82:83]
	v_add_f32_e32 v84, 1.0, v84
	v_add_f32_e32 v85, 1.0, v85
	v_pk_mul_f32 v[70:71], v[70:71], v[78:79]
	v_pk_mul_f32 v[78:79], v[80:81], v[88:89] op_sel_hi:[1,0]
	v_rcp_f32_e32 v84, v84
	v_rcp_f32_e32 v85, v85
	v_mul_f32_e32 v80, 0xbfb8aa3b, v78
	v_mul_f32_e32 v81, 0xbfb8aa3b, v79
	v_exp_f32_e32 v80, v80
	v_exp_f32_e32 v81, v81
	v_pk_mul_f32 v[74:75], v[74:75], v[84:85]
	v_pk_mul_f32 v[76:77], v[76:77], v[88:89] op_sel_hi:[1,0]
	v_pk_mul_f32 v[74:75], v[66:67], v[74:75]
	v_add_f32_e32 v66, 1.0, v80
	v_add_f32_e32 v67, 1.0, v81
	v_mul_f32_e32 v80, 0xbfb8aa3b, v76
	v_mul_f32_e32 v81, 0xbfb8aa3b, v77
	v_exp_f32_e32 v80, v80
	v_exp_f32_e32 v81, v81
	v_rcp_f32_e32 v66, v66
	v_rcp_f32_e32 v67, v67
	v_add_f32_e32 v80, 1.0, v80
	v_add_f32_e32 v81, 1.0, v81
	v_rcp_f32_e32 v80, v80
	v_rcp_f32_e32 v81, v81
	v_pk_mul_f32 v[66:67], v[78:79], v[66:67]
	v_pk_mul_f32 v[72:73], v[72:73], v[88:89] op_sel_hi:[1,0]
	v_pk_mul_f32 v[68:69], v[68:69], v[88:89] op_sel_hi:[1,0]
	v_pk_mul_f32 v[72:73], v[72:73], v[66:67]
	v_pk_mul_f32 v[66:67], v[76:77], v[80:81]
	v_add_u32_e32 v78, s19, v151
	v_pk_mul_f32 v[76:77], v[68:69], v[66:67]
	v_cvt_pk_bf16_f32 v66, v70, v71
	v_cvt_pk_bf16_f32 v68, v74, v75
	v_cvt_pk_bf16_f32 v67, v72, v73
	v_mad_i64_i32 v[72:73], s[34:35], v78, s74, v[114:115]
	s_waitcnt lgkmcnt(0)
	v_pk_mul_f32 v[62:63], v[62:63], v[234:235] op_sel_hi:[1,0]
	v_cvt_pk_bf16_f32 v69, v76, v77
	v_mul_f32_e32 v74, 0xbfb8aa3b, v62
	v_mul_f32_e32 v75, 0xbfb8aa3b, v63
	v_exp_f32_e32 v74, v74
	v_exp_f32_e32 v75, v75
	v_lshl_add_u64 v[72:73], v[72:73], 0, v[116:117]
	global_store_dwordx4 v[72:73], v[66:69], off
	v_pk_mul_f32 v[58:59], v[58:59], v[234:235] op_sel_hi:[1,0]
	v_pk_mul_f32 v[54:55], v[54:55], v[234:235] op_sel_hi:[1,0]
	v_add_f32_e32 v66, 1.0, v74
	v_add_f32_e32 v67, 1.0, v75
	v_rcp_f32_e32 v66, v66
	v_mul_f32_e32 v68, 0xbfb8aa3b, v58
	v_mul_f32_e32 v69, 0xbfb8aa3b, v59
	v_rcp_f32_e32 v67, v67
	v_exp_f32_e32 v68, v68
	v_exp_f32_e32 v69, v69
	v_pk_mul_f32 v[50:51], v[50:51], v[234:235] op_sel_hi:[1,0]
	v_pk_mul_f32 v[62:63], v[62:63], v[66:67]
	v_add_f32_e32 v68, 1.0, v68
	v_add_f32_e32 v69, 1.0, v69
	v_pk_mul_f32 v[54:55], v[54:55], v[62:63]
	v_pk_mul_f32 v[62:63], v[64:65], v[234:235] op_sel_hi:[1,0]
	v_rcp_f32_e32 v68, v68
	v_rcp_f32_e32 v69, v69
	v_mul_f32_e32 v64, 0xbfb8aa3b, v62
	v_mul_f32_e32 v65, 0xbfb8aa3b, v63
	v_exp_f32_e32 v64, v64
	v_exp_f32_e32 v65, v65
	v_pk_mul_f32 v[58:59], v[58:59], v[68:69]
	v_pk_mul_f32 v[60:61], v[60:61], v[234:235] op_sel_hi:[1,0]
	v_pk_mul_f32 v[58:59], v[50:51], v[58:59]
	v_add_f32_e32 v50, 1.0, v64
	v_add_f32_e32 v51, 1.0, v65
	v_mul_f32_e32 v64, 0xbfb8aa3b, v60
	v_mul_f32_e32 v65, 0xbfb8aa3b, v61
	v_exp_f32_e32 v64, v64
	v_exp_f32_e32 v65, v65
	v_rcp_f32_e32 v50, v50
	v_rcp_f32_e32 v51, v51
; #define LAS __attribute__((address_space(3)))
; __device__ __forceinline__ float siluf_(float x) { return x * sigmoidf_(x); }
; __device__ __forceinline__ u32x4 pack8(const f32x4 a, const f32x4 b) { u32x4 w; w.x = cvtpk(a[0], a[1]); w.y = cvtpk(a[2], a[3]); w.z = cvtpk(b[0], b[1]); w.w = cvtpk(b[2], b[3]); return w; }
;     __device__ __forceinline__ void operator()(const Acc& acc, const Unit& u, int wr, int wc, int fr, int fq) const {
;         const int col0 = u.pn * 128 + wc * 32 + 8 * fq;
;         const LAS float* rt = rtab + u.idx * 256 + wr * 64 + fr;
; #pragma unroll
;         for (int ai = 0; ai < 2; ++ai)
; #pragma unroll
;             for (int m = 0; m < 4; ++m) {
;                 const int row = u.pm * BM + ai * HALF + wr * 64 + m * 16 + fr; const float r = rt[ai * HALF + m * 16];
;                 f32x4 h0, h1;
; #pragma unroll
;                 for (int e = 0; e < 4; ++e) { h0[e] = siluf_(acc[ai][0][m][0][e] * r) * (acc[ai][1][m][0][e] * r); h1[e] = siluf_(acc[ai][0][m][1][e] * r) * (acc[ai][1][m][1][e] * r); }
;                 *(u32x4*)(H + (size_t)row * FF + col0) = pack8(h0, h1);
;             }
	v_add_f32_e32 v64, 1.0, v64
	v_add_f32_e32 v65, 1.0, v65
	v_rcp_f32_e32 v64, v64
	v_rcp_f32_e32 v65, v65
	v_pk_mul_f32 v[50:51], v[62:63], v[50:51]
	v_pk_mul_f32 v[56:57], v[56:57], v[234:235] op_sel_hi:[1,0]
	v_pk_mul_f32 v[52:53], v[52:53], v[234:235] op_sel_hi:[1,0]
	v_pk_mul_f32 v[56:57], v[56:57], v[50:51]
	v_pk_mul_f32 v[50:51], v[60:61], v[64:65]
	v_add_u32_e32 v62, 0x80, v118
	v_pk_mul_f32 v[60:61], v[52:53], v[50:51]
	v_cvt_pk_bf16_f32 v51, v56, v57
	v_mov_b32_e32 v56, v235
	v_pk_mul_f32 v[46:47], v[46:47], v[56:57] op_sel_hi:[1,0]
	v_cvt_pk_bf16_f32 v52, v58, v59
	v_mul_f32_e32 v57, 0xbfb8aa3b, v46
	v_mul_f32_e32 v58, 0xbfb8aa3b, v47
	v_exp_f32_e32 v57, v57
	v_exp_f32_e32 v58, v58
	v_cvt_pk_bf16_f32 v50, v54, v55
	v_mad_i64_i32 v[54:55], s[34:35], v62, s74, v[114:115]
	v_cvt_pk_bf16_f32 v53, v60, v61
	v_lshl_add_u64 v[54:55], v[54:55], 0, v[116:117]
	global_store_dwordx4 v[54:55], v[50:53], off
	v_pk_mul_f32 v[42:43], v[42:43], v[56:57] op_sel_hi:[1,0]
	v_pk_mul_f32 v[38:39], v[38:39], v[56:57] op_sel_hi:[1,0]
	v_add_f32_e32 v50, 1.0, v57
	v_add_f32_e32 v51, 1.0, v58
	v_rcp_f32_e32 v50, v50
	v_mul_f32_e32 v52, 0xbfb8aa3b, v42
	v_mul_f32_e32 v53, 0xbfb8aa3b, v43
	v_rcp_f32_e32 v51, v51
	v_exp_f32_e32 v52, v52
	v_exp_f32_e32 v53, v53
	v_pk_mul_f32 v[34:35], v[34:35], v[56:57] op_sel_hi:[1,0]
	v_pk_mul_f32 v[46:47], v[46:47], v[50:51]
	v_add_f32_e32 v52, 1.0, v52
	v_add_f32_e32 v53, 1.0, v53
	v_pk_mul_f32 v[38:39], v[38:39], v[46:47]
	v_pk_mul_f32 v[46:47], v[48:49], v[56:57] op_sel_hi:[1,0]
	v_rcp_f32_e32 v52, v52
	v_rcp_f32_e32 v53, v53
	v_mul_f32_e32 v48, 0xbfb8aa3b, v46
	v_mul_f32_e32 v49, 0xbfb8aa3b, v47
	v_exp_f32_e32 v48, v48
	v_exp_f32_e32 v49, v49
	v_pk_mul_f32 v[42:43], v[42:43], v[52:53]
	v_pk_mul_f32 v[44:45], v[44:45], v[56:57] op_sel_hi:[1,0]
	v_pk_mul_f32 v[42:43], v[34:35], v[42:43]
	v_add_f32_e32 v34, 1.0, v48
	v_add_f32_e32 v35, 1.0, v49
	v_mul_f32_e32 v48, 0xbfb8aa3b, v44
	v_mul_f32_e32 v49, 0xbfb8aa3b, v45
	v_exp_f32_e32 v48, v48
	v_exp_f32_e32 v49, v49
	v_rcp_f32_e32 v34, v34
	v_rcp_f32_e32 v35, v35
	v_add_f32_e32 v48, 1.0, v48
	v_add_f32_e32 v49, 1.0, v49
	v_rcp_f32_e32 v48, v48
	v_rcp_f32_e32 v49, v49
	v_pk_mul_f32 v[34:35], v[46:47], v[34:35]
	v_pk_mul_f32 v[40:41], v[40:41], v[56:57] op_sel_hi:[1,0]
	v_pk_mul_f32 v[36:37], v[36:37], v[56:57] op_sel_hi:[1,0]
	v_pk_mul_f32 v[40:41], v[40:41], v[34:35]
	v_pk_mul_f32 v[34:35], v[44:45], v[48:49]
	v_add_u32_e32 v46, 0x90, v118
	v_pk_mul_f32 v[44:45], v[36:37], v[34:35]
	v_cvt_pk_bf16_f32 v34, v38, v39
	v_cvt_pk_bf16_f32 v36, v42, v43
	v_cvt_pk_bf16_f32 v35, v40, v41
	v_mad_i64_i32 v[40:41], s[34:35], v46, s74, v[114:115]
	s_waitcnt lgkmcnt(0)
	v_pk_mul_f32 v[30:31], v[30:31], v[236:237] op_sel_hi:[1,0]
	v_cvt_pk_bf16_f32 v37, v44, v45
	v_mul_f32_e32 v42, 0xbfb8aa3b, v30
	v_mul_f32_e32 v43, 0xbfb8aa3b, v31
	v_exp_f32_e32 v42, v42
	v_exp_f32_e32 v43, v43
	v_lshl_add_u64 v[40:41], v[40:41], 0, v[116:117]
	global_store_dwordx4 v[40:41], v[34:37], off
	s_cbranch_vccnz .Lpi_p1_e
	s_add_u32 s100, s22, 0x40080
	s_addc_u32 s101, s23, 0
	v_lshl_add_u64 v[196:197], s[100:101], 0, v[138:139]
	s_add_i32 m0, s25, 0xc000
	s_nop 0
	global_load_lds_dwordx4 v[196:197], off
	v_lshl_add_u64 v[196:197], s[100:101], 0, v[140:141]
	s_add_i32 m0, s25, 0xe000
	s_nop 0
	global_load_lds_dwordx4 v[196:197], off
; __device__ __forceinline__ float siluf_(float x) { return x * sigmoidf_(x); }
; #define PG8_BAR __builtin_amdgcn_s_barrier()
; __device__ __forceinline__ u32x4 pack8(const f32x4 a, const f32x4 b) { u32x4 w; w.x = cvtpk(a[0], a[1]); w.y = cvtpk(a[2], a[3]); w.z = cvtpk(b[0], b[1]); w.w = cvtpk(b[2], b[3]); return w; }
; template <class Epi>
; __device__ __forceinline__ void gemm_phase(LAS unsigned char* lds, const Gemm g, const Sched& S, const Epi& E) {
;     ...
;         if (!has_next) break;
;         if (!(Epi::KEEP_PART0 && cur.part == 0))
; #pragma unroll
;         for (int a = 0; a < 2; ++a)
; #pragma unroll
;             for (int b = 0; b < 2; ++b)
; #pragma unroll
;                 for (int m = 0; m < 4; ++m)
; #pragma unroll
;                     for (int n = 0; n < 2; ++n) acc[a][b][m][n] = (f32x4){0.f, 0.f, 0.f, 0.f};
;         cur = nxt; cA = nA; cB = nB; ++ui;
;         if (wr == 1) PG8_BAR;
;     __device__ __forceinline__ void operator()(const Acc& acc, const Unit& u, int wr, int wc, int fr, int fq) const {
;     ...
;                 const int row = u.pm * BM + ai * HALF + wr * 64 + m * 16 + fr; const float r = rt[ai * HALF + m * 16];
;                 f32x4 h0, h1;
; #pragma unroll
;                 for (int e = 0; e < 4; ++e) { h0[e] = siluf_(acc[ai][0][m][0][e] * r) * (acc[ai][1][m][0][e] * r); h1[e] = siluf_(acc[ai][0][m][1][e] * r) * (acc[ai][1][m][1][e] * r); }
;                 *(u32x4*)(H + (size_t)row * FF + col0) = pack8(h0, h1);
.Lpi_p1_e:
	v_pk_mul_f32 v[26:27], v[26:27], v[236:237] op_sel_hi:[1,0]
	v_pk_mul_f32 v[22:23], v[22:23], v[236:237] op_sel_hi:[1,0]
	v_add_f32_e32 v34, 1.0, v42
	v_add_f32_e32 v35, 1.0, v43
	v_rcp_f32_e32 v34, v34
	v_mul_f32_e32 v36, 0xbfb8aa3b, v26
	v_mul_f32_e32 v37, 0xbfb8aa3b, v27
	v_rcp_f32_e32 v35, v35
	v_exp_f32_e32 v36, v36
	v_exp_f32_e32 v37, v37
	v_pk_mul_f32 v[18:19], v[18:19], v[236:237] op_sel_hi:[1,0]
	v_pk_mul_f32 v[30:31], v[30:31], v[34:35]
	v_add_f32_e32 v36, 1.0, v36
	v_add_f32_e32 v37, 1.0, v37
	v_pk_mul_f32 v[22:23], v[22:23], v[30:31]
	v_pk_mul_f32 v[30:31], v[32:33], v[236:237] op_sel_hi:[1,0]
	v_rcp_f32_e32 v36, v36
	v_rcp_f32_e32 v37, v37
	v_mul_f32_e32 v32, 0xbfb8aa3b, v30
	v_mul_f32_e32 v33, 0xbfb8aa3b, v31
	v_exp_f32_e32 v32, v32
	v_exp_f32_e32 v33, v33
	v_pk_mul_f32 v[26:27], v[26:27], v[36:37]
	v_pk_mul_f32 v[28:29], v[28:29], v[236:237] op_sel_hi:[1,0]
	v_pk_mul_f32 v[26:27], v[18:19], v[26:27]
	v_add_f32_e32 v18, 1.0, v32
	v_add_f32_e32 v19, 1.0, v33
	v_mul_f32_e32 v32, 0xbfb8aa3b, v28
	v_mul_f32_e32 v33, 0xbfb8aa3b, v29
	v_exp_f32_e32 v32, v32
	v_exp_f32_e32 v33, v33
	v_rcp_f32_e32 v18, v18
	v_rcp_f32_e32 v19, v19
	v_add_f32_e32 v32, 1.0, v32
	v_add_f32_e32 v33, 1.0, v33
	v_rcp_f32_e32 v32, v32
	v_rcp_f32_e32 v33, v33
	v_pk_mul_f32 v[18:19], v[30:31], v[18:19]
	v_pk_mul_f32 v[24:25], v[24:25], v[236:237] op_sel_hi:[1,0]
	v_pk_mul_f32 v[20:21], v[20:21], v[236:237] op_sel_hi:[1,0]
	v_pk_mul_f32 v[24:25], v[24:25], v[18:19]
	v_pk_mul_f32 v[18:19], v[28:29], v[32:33]
	v_add_u32_e32 v30, 0xa0, v118
	v_pk_mul_f32 v[28:29], v[20:21], v[18:19]
	v_cvt_pk_bf16_f32 v19, v24, v25
	v_mov_b32_e32 v24, v237
	v_pk_mul_f32 v[14:15], v[14:15], v[24:25] op_sel_hi:[1,0]
	v_cvt_pk_bf16_f32 v20, v26, v27
	v_mul_f32_e32 v25, 0xbfb8aa3b, v14
	v_mul_f32_e32 v26, 0xbfb8aa3b, v15
	v_exp_f32_e32 v25, v25
	v_exp_f32_e32 v26, v26
	v_cvt_pk_bf16_f32 v18, v22, v23
	v_mad_i64_i32 v[22:23], s[34:35], v30, s74, v[114:115]
	v_cvt_pk_bf16_f32 v21, v28, v29
	v_lshl_add_u64 v[22:23], v[22:23], 0, v[116:117]
	global_store_dwordx4 v[22:23], v[18:21], off
	v_pk_mul_f32 v[10:11], v[10:11], v[24:25] op_sel_hi:[1,0]
	v_pk_mul_f32 v[6:7], v[6:7], v[24:25] op_sel_hi:[1,0]
	v_add_f32_e32 v18, 1.0, v25
	v_add_f32_e32 v19, 1.0, v26
	v_rcp_f32_e32 v18, v18
	v_mul_f32_e32 v20, 0xbfb8aa3b, v10
	v_mul_f32_e32 v21, 0xbfb8aa3b, v11
	v_rcp_f32_e32 v19, v19
	v_exp_f32_e32 v20, v20
	v_exp_f32_e32 v21, v21
	v_pk_mul_f32 v[2:3], v[2:3], v[24:25] op_sel_hi:[1,0]
	v_pk_mul_f32 v[14:15], v[14:15], v[18:19]
	v_add_f32_e32 v20, 1.0, v20
	v_add_f32_e32 v21, 1.0, v21
	v_pk_mul_f32 v[6:7], v[6:7], v[14:15]
	v_pk_mul_f32 v[14:15], v[16:17], v[24:25] op_sel_hi:[1,0]
	v_rcp_f32_e32 v20, v20
	v_rcp_f32_e32 v21, v21
	v_mul_f32_e32 v16, 0xbfb8aa3b, v14
	v_mul_f32_e32 v17, 0xbfb8aa3b, v15
	v_exp_f32_e32 v16, v16
	v_exp_f32_e32 v17, v17
	v_pk_mul_f32 v[10:11], v[10:11], v[20:21]
	v_pk_mul_f32 v[12:13], v[12:13], v[24:25] op_sel_hi:[1,0]
	v_pk_mul_f32 v[10:11], v[2:3], v[10:11]
	v_add_f32_e32 v2, 1.0, v16
	v_add_f32_e32 v3, 1.0, v17
	v_mul_f32_e32 v16, 0xbfb8aa3b, v12
	v_mul_f32_e32 v17, 0xbfb8aa3b, v13
	v_exp_f32_e32 v16, v16
	v_exp_f32_e32 v17, v17
	v_rcp_f32_e32 v2, v2
	v_rcp_f32_e32 v3, v3
	v_add_f32_e32 v16, 1.0, v16
	v_add_f32_e32 v17, 1.0, v17
	v_rcp_f32_e32 v16, v16
	v_rcp_f32_e32 v17, v17
	v_pk_mul_f32 v[2:3], v[14:15], v[2:3]
	v_pk_mul_f32 v[8:9], v[8:9], v[24:25] op_sel_hi:[1,0]
	v_pk_mul_f32 v[4:5], v[4:5], v[24:25] op_sel_hi:[1,0]
	v_pk_mul_f32 v[8:9], v[8:9], v[2:3]
	v_pk_mul_f32 v[2:3], v[12:13], v[16:17]
	v_add_u32_e32 v14, 0xb0, v118
	v_pk_mul_f32 v[12:13], v[4:5], v[2:3]
	v_cvt_pk_bf16_f32 v2, v6, v7
	v_mad_i64_i32 v[6:7], s[34:35], v14, s74, v[114:115]
	v_cvt_pk_bf16_f32 v3, v8, v9
	v_cvt_pk_bf16_f32 v4, v10, v11
	v_cvt_pk_bf16_f32 v5, v12, v13
	v_lshl_add_u64 v[6:7], v[6:7], 0, v[116:117]
	s_mov_b64 s[0:1], -1
	global_store_dwordx4 v[6:7], v[2:5], off
	s_cbranch_vccnz .LBB0_576
	s_andn2_b64 vcc, exec, s[4:5]
	s_cbranch_vccnz .LBB0_575
	s_barrier
	s_branch .LBB0_575

; #define LAS __attribute__((address_space(3)))
; __device__ __forceinline__ float siluf_(float x) { return x * sigmoidf_(x); }
; __device__ __forceinline__ u32x4 pack8(const f32x4 a, const f32x4 b) { u32x4 w; w.x = cvtpk(a[0], a[1]); w.y = cvtpk(a[2], a[3]); w.z = cvtpk(b[0], b[1]); w.w = cvtpk(b[2], b[3]); return w; }
;     __device__ __forceinline__ void operator()(const Acc& acc, const Unit& u, int wr, int wc, int fr, int fq) const {
;         const int col0 = u.pn * 128 + wc * 32 + 8 * fq;
;         const LAS float* rt = rtab + u.idx * 256 + wr * 64 + fr;
; #pragma unroll
;         for (int ai = 0; ai < 2; ++ai)
; #pragma unroll
;             for (int m = 0; m < 4; ++m) {
;                 const int row = u.pm * BM + ai * HALF + wr * 64 + m * 16 + fr; const float r = rt[ai * HALF + m * 16];
;                 f32x4 h0, h1;
; #pragma unroll
;                 for (int e = 0; e < 4; ++e) { h0[e] = siluf_(acc[ai][0][m][0][e] * r) * (acc[ai][1][m][0][e] * r); h1[e] = siluf_(acc[ai][0][m][1][e] * r) * (acc[ai][1][m][1][e] * r); }
;                 *(u32x4*)(H + (size_t)row * FF + col0) = pack8(h0, h1);
;             }
.LBB0_1721:
	v_lshl_add_u32 v156, s43, 10, v148
	ds_read2_b32 v[158:159], v156 offset1:16
	ds_read2_b32 v[232:233], v156 offset0:32 offset1:48
	ds_read2_b32 v[234:235], v156 offset0:128 offset1:144
	ds_read2_b32 v[236:237], v156 offset0:160 offset1:176
	v_lshl_or_b32 v160, s44, 7, v152
	s_lshl_b32 s11, s20, 8
	v_ashrrev_i32_e32 v161, 31, v160
	s_andn2_b64 vcc, exec, s[0:1]
	s_waitcnt lgkmcnt(0)
	v_pk_mul_f32 v[126:127], v[126:127], v[158:159] op_sel_hi:[1,0]
	v_pk_mul_f32 v[122:123], v[122:123], v[158:159] op_sel_hi:[1,0]
	v_mul_f32_e32 v157, 0xbfb8aa3b, v126
	v_mul_f32_e32 v162, 0xbfb8aa3b, v127
	v_exp_f32_e32 v157, v157
	v_exp_f32_e32 v162, v162
	v_mul_f32_e32 v163, 0xbfb8aa3b, v122
	v_pk_mul_f32 v[118:119], v[118:119], v[158:159] op_sel_hi:[1,0]
	v_add_f32_e32 v157, 1.0, v157
	v_add_f32_e32 v164, 1.0, v162
	v_rcp_f32_e32 v162, v157
	v_exp_f32_e32 v157, v163
	v_mul_f32_e32 v163, 0xbfb8aa3b, v123
	v_exp_f32_e32 v165, v163
	v_rcp_f32_e32 v163, v164
	v_add_f32_e32 v157, 1.0, v157
	v_rcp_f32_e32 v164, v157
	v_add_f32_e32 v157, 1.0, v165
	v_rcp_f32_e32 v165, v157
	v_pk_mul_f32 v[126:127], v[126:127], v[162:163]
	v_pk_mul_f32 v[114:115], v[114:115], v[158:159] op_sel_hi:[1,0]
	v_pk_mul_f32 v[126:127], v[118:119], v[126:127]
	v_pk_mul_f32 v[118:119], v[122:123], v[164:165]
	v_pk_mul_f32 v[122:123], v[128:129], v[158:159] op_sel_hi:[1,0]
	v_pk_mul_f32 v[124:125], v[124:125], v[158:159] op_sel_hi:[1,0]
	v_mul_f32_e32 v128, 0xbfb8aa3b, v122
	v_mul_f32_e32 v129, 0xbfb8aa3b, v123
	v_exp_f32_e32 v128, v128
	v_exp_f32_e32 v129, v129
	v_pk_mul_f32 v[114:115], v[114:115], v[118:119]
	v_pk_mul_f32 v[120:121], v[120:121], v[158:159] op_sel_hi:[1,0]
	v_add_f32_e32 v118, 1.0, v128
	v_add_f32_e32 v119, 1.0, v129
	v_mul_f32_e32 v128, 0xbfb8aa3b, v124
	v_mul_f32_e32 v129, 0xbfb8aa3b, v125
	v_exp_f32_e32 v128, v128
	v_exp_f32_e32 v129, v129
	v_rcp_f32_e32 v118, v118
	v_rcp_f32_e32 v119, v119
	v_add_f32_e32 v128, 1.0, v128
	v_add_f32_e32 v129, 1.0, v129
	v_rcp_f32_e32 v128, v128
	v_rcp_f32_e32 v129, v129
	v_pk_mul_f32 v[118:119], v[122:123], v[118:119]
	v_pk_mul_f32 v[116:117], v[116:117], v[158:159] op_sel_hi:[1,0]
	v_pk_mul_f32 v[122:123], v[120:121], v[118:119]
	v_cvt_pk_bf16_f32 v120, v126, v127
	v_mov_b32_e32 v126, v159
	v_pk_mul_f32 v[110:111], v[110:111], v[126:127] op_sel_hi:[1,0]
	v_pk_mul_f32 v[118:119], v[124:125], v[128:129]
	v_mul_f32_e32 v127, 0xbfb8aa3b, v111
	v_pk_mul_f32 v[116:117], v[116:117], v[118:119]
	v_mul_f32_e32 v119, 0xbfb8aa3b, v110
	v_exp_f32_e32 v127, v127
	v_exp_f32_e32 v119, v119
	v_add_u32_e32 v118, s11, v146
	v_cvt_pk_bf16_f32 v121, v122, v123
	v_cvt_pk_bf16_f32 v122, v114, v115
	v_mov_b64_e32 v[114:115], s[80:81]
	v_cvt_pk_bf16_f32 v123, v116, v117
	v_mad_i64_i32 v[124:125], s[22:23], v118, s38, v[114:115]
	v_lshlrev_b64 v[116:117], 1, v[160:161]
	v_lshl_add_u64 v[124:125], v[124:125], 0, v[116:117]
	v_pk_mul_f32 v[106:107], v[106:107], v[126:127] op_sel_hi:[1,0]
	global_store_dwordx4 v[124:125], v[120:123], off
	v_add_f32_e32 v119, 1.0, v119
	v_pk_mul_f32 v[102:103], v[102:103], v[126:127] op_sel_hi:[1,0]
	v_mul_f32_e32 v121, 0xbfb8aa3b, v106
	v_rcp_f32_e32 v120, v119
	v_add_f32_e32 v119, 1.0, v127
	v_exp_f32_e32 v122, v121
	v_mul_f32_e32 v121, 0xbfb8aa3b, v107
	v_exp_f32_e32 v123, v121
	v_rcp_f32_e32 v121, v119
	v_add_f32_e32 v119, 1.0, v122
	v_rcp_f32_e32 v122, v119
	v_add_f32_e32 v119, 1.0, v123
	v_pk_mul_f32 v[110:111], v[110:111], v[120:121]
	v_rcp_f32_e32 v123, v119
	v_pk_mul_f32 v[102:103], v[102:103], v[110:111]
	v_pk_mul_f32 v[110:111], v[112:113], v[126:127] op_sel_hi:[1,0]
	v_pk_mul_f32 v[98:99], v[98:99], v[126:127] op_sel_hi:[1,0]
	v_mul_f32_e32 v112, 0xbfb8aa3b, v110
	v_mul_f32_e32 v113, 0xbfb8aa3b, v111
	v_exp_f32_e32 v112, v112
	v_exp_f32_e32 v113, v113
	v_pk_mul_f32 v[106:107], v[106:107], v[122:123]
	v_pk_mul_f32 v[108:109], v[108:109], v[126:127] op_sel_hi:[1,0]
	v_pk_mul_f32 v[106:107], v[98:99], v[106:107]
	v_add_f32_e32 v98, 1.0, v112
	v_add_f32_e32 v99, 1.0, v113
	v_mul_f32_e32 v112, 0xbfb8aa3b, v108
	v_mul_f32_e32 v113, 0xbfb8aa3b, v109
	v_exp_f32_e32 v112, v112
	v_exp_f32_e32 v113, v113
	v_rcp_f32_e32 v98, v98
	v_rcp_f32_e32 v99, v99
	v_add_f32_e32 v112, 1.0, v112
	v_add_f32_e32 v113, 1.0, v113
	v_rcp_f32_e32 v112, v112
	v_rcp_f32_e32 v113, v113
	v_pk_mul_f32 v[98:99], v[110:111], v[98:99]
	v_pk_mul_f32 v[104:105], v[104:105], v[126:127] op_sel_hi:[1,0]
	v_pk_mul_f32 v[100:101], v[100:101], v[126:127] op_sel_hi:[1,0]
	v_pk_mul_f32 v[104:105], v[104:105], v[98:99]
	v_pk_mul_f32 v[98:99], v[108:109], v[112:113]
	v_add_u32_e32 v110, s11, v149
	v_pk_mul_f32 v[108:109], v[100:101], v[98:99]
	v_cvt_pk_bf16_f32 v98, v102, v103
	v_cvt_pk_bf16_f32 v100, v106, v107
	v_cvt_pk_bf16_f32 v99, v104, v105
	v_mad_i64_i32 v[104:105], s[22:23], v110, s38, v[114:115]
	s_waitcnt lgkmcnt(0)
; __device__ __forceinline__ float siluf_(float x) { return x * sigmoidf_(x); }
; __device__ __forceinline__ u32x4 pack8(const f32x4 a, const f32x4 b) { u32x4 w; w.x = cvtpk(a[0], a[1]); w.y = cvtpk(a[2], a[3]); w.z = cvtpk(b[0], b[1]); w.w = cvtpk(b[2], b[3]); return w; }
;     __device__ __forceinline__ void operator()(const Acc& acc, const Unit& u, int wr, int wc, int fr, int fq) const {
;     ...
;                 const int row = u.pm * BM + ai * HALF + wr * 64 + m * 16 + fr; const float r = rt[ai * HALF + m * 16];
;                 f32x4 h0, h1;
; #pragma unroll
;                 for (int e = 0; e < 4; ++e) { h0[e] = siluf_(acc[ai][0][m][0][e] * r) * (acc[ai][1][m][0][e] * r); h1[e] = siluf_(acc[ai][0][m][1][e] * r) * (acc[ai][1][m][1][e] * r); }
;                 *(u32x4*)(H + (size_t)row * FF + col0) = pack8(h0, h1);
	v_pk_mul_f32 v[94:95], v[94:95], v[232:233] op_sel_hi:[1,0]
	v_cvt_pk_bf16_f32 v101, v108, v109
	v_mul_f32_e32 v106, 0xbfb8aa3b, v94
	v_mul_f32_e32 v107, 0xbfb8aa3b, v95
	v_exp_f32_e32 v106, v106
	v_exp_f32_e32 v107, v107
	v_lshl_add_u64 v[104:105], v[104:105], 0, v[116:117]
	global_store_dwordx4 v[104:105], v[98:101], off
	v_pk_mul_f32 v[90:91], v[90:91], v[232:233] op_sel_hi:[1,0]
	v_pk_mul_f32 v[86:87], v[86:87], v[232:233] op_sel_hi:[1,0]
	v_add_f32_e32 v98, 1.0, v106
	v_add_f32_e32 v99, 1.0, v107
	v_rcp_f32_e32 v98, v98
	v_mul_f32_e32 v100, 0xbfb8aa3b, v90
	v_mul_f32_e32 v101, 0xbfb8aa3b, v91
	v_rcp_f32_e32 v99, v99
	v_exp_f32_e32 v100, v100
	v_exp_f32_e32 v101, v101
	v_pk_mul_f32 v[82:83], v[82:83], v[232:233] op_sel_hi:[1,0]
	v_pk_mul_f32 v[94:95], v[94:95], v[98:99]
	v_add_f32_e32 v100, 1.0, v100
	v_add_f32_e32 v101, 1.0, v101
	v_pk_mul_f32 v[86:87], v[86:87], v[94:95]
	v_pk_mul_f32 v[94:95], v[96:97], v[232:233] op_sel_hi:[1,0]
	v_rcp_f32_e32 v100, v100
	v_rcp_f32_e32 v101, v101
	v_mul_f32_e32 v96, 0xbfb8aa3b, v94
	v_mul_f32_e32 v97, 0xbfb8aa3b, v95
	v_exp_f32_e32 v96, v96
	v_exp_f32_e32 v97, v97
	v_pk_mul_f32 v[90:91], v[90:91], v[100:101]
	v_pk_mul_f32 v[92:93], v[92:93], v[232:233] op_sel_hi:[1,0]
	v_pk_mul_f32 v[90:91], v[82:83], v[90:91]
	v_add_f32_e32 v82, 1.0, v96
	v_add_f32_e32 v83, 1.0, v97
	v_mul_f32_e32 v96, 0xbfb8aa3b, v92
	v_mul_f32_e32 v97, 0xbfb8aa3b, v93
	v_exp_f32_e32 v96, v96
	v_exp_f32_e32 v97, v97
	v_rcp_f32_e32 v82, v82
	v_rcp_f32_e32 v83, v83
	v_add_f32_e32 v96, 1.0, v96
	v_add_f32_e32 v97, 1.0, v97
	v_rcp_f32_e32 v96, v96
	v_rcp_f32_e32 v97, v97
	v_pk_mul_f32 v[82:83], v[94:95], v[82:83]
	v_pk_mul_f32 v[88:89], v[88:89], v[232:233] op_sel_hi:[1,0]
	v_pk_mul_f32 v[84:85], v[84:85], v[232:233] op_sel_hi:[1,0]
	v_pk_mul_f32 v[88:89], v[88:89], v[82:83]
	v_pk_mul_f32 v[82:83], v[92:93], v[96:97]
	v_add_u32_e32 v94, s11, v150
	v_pk_mul_f32 v[92:93], v[84:85], v[82:83]
	v_cvt_pk_bf16_f32 v83, v88, v89
	v_mov_b32_e32 v88, v233
	v_pk_mul_f32 v[78:79], v[78:79], v[88:89] op_sel_hi:[1,0]
	v_cvt_pk_bf16_f32 v84, v90, v91
	v_mul_f32_e32 v89, 0xbfb8aa3b, v78
	v_mul_f32_e32 v90, 0xbfb8aa3b, v79
	v_exp_f32_e32 v89, v89
	v_exp_f32_e32 v90, v90
	v_cvt_pk_bf16_f32 v82, v86, v87
	v_mad_i64_i32 v[86:87], s[22:23], v94, s38, v[114:115]
	v_cvt_pk_bf16_f32 v85, v92, v93
	v_lshl_add_u64 v[86:87], v[86:87], 0, v[116:117]
	global_store_dwordx4 v[86:87], v[82:85], off
	v_pk_mul_f32 v[74:75], v[74:75], v[88:89] op_sel_hi:[1,0]
	v_pk_mul_f32 v[70:71], v[70:71], v[88:89] op_sel_hi:[1,0]
	v_add_f32_e32 v82, 1.0, v89
	v_add_f32_e32 v83, 1.0, v90
	v_rcp_f32_e32 v82, v82
	v_mul_f32_e32 v84, 0xbfb8aa3b, v74
	v_mul_f32_e32 v85, 0xbfb8aa3b, v75
	v_rcp_f32_e32 v83, v83
	v_exp_f32_e32 v84, v84
	v_exp_f32_e32 v85, v85
	v_pk_mul_f32 v[66:67], v[66:67], v[88:89] op_sel_hi:[1,0]
	v_pk_mul_f32 v[78:79], v[78:79], v[82:83]
	v_add_f32_e32 v84, 1.0, v84
	v_add_f32_e32 v85, 1.0, v85
	v_pk_mul_f32 v[70:71], v[70:71], v[78:79]
	v_pk_mul_f32 v[78:79], v[80:81], v[88:89] op_sel_hi:[1,0]
	v_rcp_f32_e32 v84, v84
	v_rcp_f32_e32 v85, v85
	v_mul_f32_e32 v80, 0xbfb8aa3b, v78
	v_mul_f32_e32 v81, 0xbfb8aa3b, v79
	v_exp_f32_e32 v80, v80
	v_exp_f32_e32 v81, v81
	v_pk_mul_f32 v[74:75], v[74:75], v[84:85]
	v_pk_mul_f32 v[76:77], v[76:77], v[88:89] op_sel_hi:[1,0]
	v_pk_mul_f32 v[74:75], v[66:67], v[74:75]
	v_add_f32_e32 v66, 1.0, v80
	v_add_f32_e32 v67, 1.0, v81
	v_mul_f32_e32 v80, 0xbfb8aa3b, v76
	v_mul_f32_e32 v81, 0xbfb8aa3b, v77
	v_exp_f32_e32 v80, v80
	v_exp_f32_e32 v81, v81
	v_rcp_f32_e32 v66, v66
	v_rcp_f32_e32 v67, v67
	v_add_f32_e32 v80, 1.0, v80
	v_add_f32_e32 v81, 1.0, v81
	v_rcp_f32_e32 v80, v80
	v_rcp_f32_e32 v81, v81
	v_pk_mul_f32 v[66:67], v[78:79], v[66:67]
	v_pk_mul_f32 v[72:73], v[72:73], v[88:89] op_sel_hi:[1,0]
	v_pk_mul_f32 v[68:69], v[68:69], v[88:89] op_sel_hi:[1,0]
	v_pk_mul_f32 v[72:73], v[72:73], v[66:67]
	v_pk_mul_f32 v[66:67], v[76:77], v[80:81]
	v_add_u32_e32 v78, s11, v151
	v_pk_mul_f32 v[76:77], v[68:69], v[66:67]
	v_cvt_pk_bf16_f32 v66, v70, v71
	v_cvt_pk_bf16_f32 v68, v74, v75
	v_cvt_pk_bf16_f32 v67, v72, v73
	v_mad_i64_i32 v[72:73], s[22:23], v78, s38, v[114:115]
	s_waitcnt lgkmcnt(0)
	v_pk_mul_f32 v[62:63], v[62:63], v[234:235] op_sel_hi:[1,0]
	v_cvt_pk_bf16_f32 v69, v76, v77
	v_mul_f32_e32 v74, 0xbfb8aa3b, v62
	v_mul_f32_e32 v75, 0xbfb8aa3b, v63
	v_exp_f32_e32 v74, v74
	v_exp_f32_e32 v75, v75
	v_lshl_add_u64 v[72:73], v[72:73], 0, v[116:117]
	global_store_dwordx4 v[72:73], v[66:69], off
	v_pk_mul_f32 v[58:59], v[58:59], v[234:235] op_sel_hi:[1,0]
	v_pk_mul_f32 v[54:55], v[54:55], v[234:235] op_sel_hi:[1,0]
	v_add_f32_e32 v66, 1.0, v74
	v_add_f32_e32 v67, 1.0, v75
	v_rcp_f32_e32 v66, v66
	v_mul_f32_e32 v68, 0xbfb8aa3b, v58
	v_mul_f32_e32 v69, 0xbfb8aa3b, v59
	v_rcp_f32_e32 v67, v67
	v_exp_f32_e32 v68, v68
	v_exp_f32_e32 v69, v69
	v_pk_mul_f32 v[50:51], v[50:51], v[234:235] op_sel_hi:[1,0]
	v_pk_mul_f32 v[62:63], v[62:63], v[66:67]
	v_add_f32_e32 v68, 1.0, v68
	v_add_f32_e32 v69, 1.0, v69
	v_pk_mul_f32 v[54:55], v[54:55], v[62:63]
	v_pk_mul_f32 v[62:63], v[64:65], v[234:235] op_sel_hi:[1,0]
	v_rcp_f32_e32 v68, v68
	v_rcp_f32_e32 v69, v69
	v_mul_f32_e32 v64, 0xbfb8aa3b, v62
	v_mul_f32_e32 v65, 0xbfb8aa3b, v63
	v_exp_f32_e32 v64, v64
	v_exp_f32_e32 v65, v65
	v_pk_mul_f32 v[58:59], v[58:59], v[68:69]
	v_pk_mul_f32 v[60:61], v[60:61], v[234:235] op_sel_hi:[1,0]
	v_pk_mul_f32 v[58:59], v[50:51], v[58:59]
	v_add_f32_e32 v50, 1.0, v64
	v_add_f32_e32 v51, 1.0, v65
	v_mul_f32_e32 v64, 0xbfb8aa3b, v60
	v_mul_f32_e32 v65, 0xbfb8aa3b, v61
	v_exp_f32_e32 v64, v64
	v_exp_f32_e32 v65, v65
	v_rcp_f32_e32 v50, v50
	v_rcp_f32_e32 v51, v51
; #define LAS __attribute__((address_space(3)))
; __device__ __forceinline__ float siluf_(float x) { return x * sigmoidf_(x); }
; __device__ __forceinline__ u32x4 pack8(const f32x4 a, const f32x4 b) { u32x4 w; w.x = cvtpk(a[0], a[1]); w.y = cvtpk(a[2], a[3]); w.z = cvtpk(b[0], b[1]); w.w = cvtpk(b[2], b[3]); return w; }
;     __device__ __forceinline__ void operator()(const Acc& acc, const Unit& u, int wr, int wc, int fr, int fq) const {
;         const int col0 = u.pn * 128 + wc * 32 + 8 * fq;
;         const LAS float* rt = rtab + u.idx * 256 + wr * 64 + fr;
; #pragma unroll
;         for (int ai = 0; ai < 2; ++ai)
; #pragma unroll
;             for (int m = 0; m < 4; ++m) {
;                 const int row = u.pm * BM + ai * HALF + wr * 64 + m * 16 + fr; const float r = rt[ai * HALF + m * 16];
;                 f32x4 h0, h1;
; #pragma unroll
;                 for (int e = 0; e < 4; ++e) { h0[e] = siluf_(acc[ai][0][m][0][e] * r) * (acc[ai][1][m][0][e] * r); h1[e] = siluf_(acc[ai][0][m][1][e] * r) * (acc[ai][1][m][1][e] * r); }
;                 *(u32x4*)(H + (size_t)row * FF + col0) = pack8(h0, h1);
;             }
	v_add_f32_e32 v64, 1.0, v64
	v_add_f32_e32 v65, 1.0, v65
	v_rcp_f32_e32 v64, v64
	v_rcp_f32_e32 v65, v65
	v_pk_mul_f32 v[50:51], v[62:63], v[50:51]
	v_pk_mul_f32 v[56:57], v[56:57], v[234:235] op_sel_hi:[1,0]
	v_pk_mul_f32 v[52:53], v[52:53], v[234:235] op_sel_hi:[1,0]
	v_pk_mul_f32 v[56:57], v[56:57], v[50:51]
	v_pk_mul_f32 v[50:51], v[60:61], v[64:65]
	v_add_u32_e32 v62, 0x80, v118
	v_pk_mul_f32 v[60:61], v[52:53], v[50:51]
	v_cvt_pk_bf16_f32 v51, v56, v57
	v_mov_b32_e32 v56, v235
	v_pk_mul_f32 v[46:47], v[46:47], v[56:57] op_sel_hi:[1,0]
	v_cvt_pk_bf16_f32 v52, v58, v59
	v_mul_f32_e32 v57, 0xbfb8aa3b, v46
	v_mul_f32_e32 v58, 0xbfb8aa3b, v47
	v_exp_f32_e32 v57, v57
	v_exp_f32_e32 v58, v58
	v_cvt_pk_bf16_f32 v50, v54, v55
	v_mad_i64_i32 v[54:55], s[22:23], v62, s38, v[114:115]
	v_cvt_pk_bf16_f32 v53, v60, v61
	v_lshl_add_u64 v[54:55], v[54:55], 0, v[116:117]
	global_store_dwordx4 v[54:55], v[50:53], off
	v_pk_mul_f32 v[42:43], v[42:43], v[56:57] op_sel_hi:[1,0]
	v_pk_mul_f32 v[38:39], v[38:39], v[56:57] op_sel_hi:[1,0]
	v_add_f32_e32 v50, 1.0, v57
	v_add_f32_e32 v51, 1.0, v58
	v_rcp_f32_e32 v50, v50
	v_mul_f32_e32 v52, 0xbfb8aa3b, v42
	v_mul_f32_e32 v53, 0xbfb8aa3b, v43
	v_rcp_f32_e32 v51, v51
	v_exp_f32_e32 v52, v52
	v_exp_f32_e32 v53, v53
	v_pk_mul_f32 v[34:35], v[34:35], v[56:57] op_sel_hi:[1,0]
	v_pk_mul_f32 v[46:47], v[46:47], v[50:51]
	v_add_f32_e32 v52, 1.0, v52
	v_add_f32_e32 v53, 1.0, v53
	v_pk_mul_f32 v[38:39], v[38:39], v[46:47]
	v_pk_mul_f32 v[46:47], v[48:49], v[56:57] op_sel_hi:[1,0]
	v_rcp_f32_e32 v52, v52
	v_rcp_f32_e32 v53, v53
	v_mul_f32_e32 v48, 0xbfb8aa3b, v46
	v_mul_f32_e32 v49, 0xbfb8aa3b, v47
	v_exp_f32_e32 v48, v48
	v_exp_f32_e32 v49, v49
	v_pk_mul_f32 v[42:43], v[42:43], v[52:53]
	v_pk_mul_f32 v[44:45], v[44:45], v[56:57] op_sel_hi:[1,0]
	v_pk_mul_f32 v[42:43], v[34:35], v[42:43]
	v_add_f32_e32 v34, 1.0, v48
	v_add_f32_e32 v35, 1.0, v49
	v_mul_f32_e32 v48, 0xbfb8aa3b, v44
	v_mul_f32_e32 v49, 0xbfb8aa3b, v45
	v_exp_f32_e32 v48, v48
	v_exp_f32_e32 v49, v49
	v_rcp_f32_e32 v34, v34
	v_rcp_f32_e32 v35, v35
	v_add_f32_e32 v48, 1.0, v48
	v_add_f32_e32 v49, 1.0, v49
	v_rcp_f32_e32 v48, v48
	v_rcp_f32_e32 v49, v49
	v_pk_mul_f32 v[34:35], v[46:47], v[34:35]
	v_pk_mul_f32 v[40:41], v[40:41], v[56:57] op_sel_hi:[1,0]
	v_pk_mul_f32 v[36:37], v[36:37], v[56:57] op_sel_hi:[1,0]
	v_pk_mul_f32 v[40:41], v[40:41], v[34:35]
	v_pk_mul_f32 v[34:35], v[44:45], v[48:49]
	v_add_u32_e32 v46, 0x90, v118
	v_pk_mul_f32 v[44:45], v[36:37], v[34:35]
	v_cvt_pk_bf16_f32 v34, v38, v39
	v_cvt_pk_bf16_f32 v36, v42, v43
	v_cvt_pk_bf16_f32 v35, v40, v41
	v_mad_i64_i32 v[40:41], s[22:23], v46, s38, v[114:115]
	s_waitcnt lgkmcnt(0)
	v_pk_mul_f32 v[30:31], v[30:31], v[236:237] op_sel_hi:[1,0]
	v_cvt_pk_bf16_f32 v37, v44, v45
	v_mul_f32_e32 v42, 0xbfb8aa3b, v30
	v_mul_f32_e32 v43, 0xbfb8aa3b, v31
	v_exp_f32_e32 v42, v42
	v_exp_f32_e32 v43, v43
	v_lshl_add_u64 v[40:41], v[40:41], 0, v[116:117]
	global_store_dwordx4 v[40:41], v[34:37], off
	s_cbranch_vccnz .Lpi_p9_e
	s_add_u32 s100, s16, 0x40080
	s_addc_u32 s101, s17, 0
	v_lshl_add_u64 v[196:197], s[100:101], 0, v[138:139]
	s_add_i32 m0, s21, 0xc000
	s_nop 0
	global_load_lds_dwordx4 v[196:197], off
	v_lshl_add_u64 v[196:197], s[100:101], 0, v[140:141]
	s_add_i32 m0, s21, 0xe000
	s_nop 0
	global_load_lds_dwordx4 v[196:197], off
; __device__ __forceinline__ float siluf_(float x) { return x * sigmoidf_(x); }
; #define PG8_BAR __builtin_amdgcn_s_barrier()
; __device__ __forceinline__ u32x4 pack8(const f32x4 a, const f32x4 b) { u32x4 w; w.x = cvtpk(a[0], a[1]); w.y = cvtpk(a[2], a[3]); w.z = cvtpk(b[0], b[1]); w.w = cvtpk(b[2], b[3]); return w; }
; template <class Epi>
; __device__ __forceinline__ void gemm_phase(LAS unsigned char* lds, const Gemm g, const Sched& S, const Epi& E) {
;     ...
;         if (!has_next) break;
;         if (!(Epi::KEEP_PART0 && cur.part == 0))
; #pragma unroll
;         for (int a = 0; a < 2; ++a)
; #pragma unroll
;             for (int b = 0; b < 2; ++b)
; #pragma unroll
;                 for (int m = 0; m < 4; ++m)
; #pragma unroll
;                     for (int n = 0; n < 2; ++n) acc[a][b][m][n] = (f32x4){0.f, 0.f, 0.f, 0.f};
;         cur = nxt; cA = nA; cB = nB; ++ui;
;         if (wr == 1) PG8_BAR;
;     __device__ __forceinline__ void operator()(const Acc& acc, const Unit& u, int wr, int wc, int fr, int fq) const {
;     ...
;                 const int row = u.pm * BM + ai * HALF + wr * 64 + m * 16 + fr; const float r = rt[ai * HALF + m * 16];
;                 f32x4 h0, h1;
; #pragma unroll
;                 for (int e = 0; e < 4; ++e) { h0[e] = siluf_(acc[ai][0][m][0][e] * r) * (acc[ai][1][m][0][e] * r); h1[e] = siluf_(acc[ai][0][m][1][e] * r) * (acc[ai][1][m][1][e] * r); }
;                 *(u32x4*)(H + (size_t)row * FF + col0) = pack8(h0, h1);
.Lpi_p9_e:
	v_pk_mul_f32 v[26:27], v[26:27], v[236:237] op_sel_hi:[1,0]
	v_pk_mul_f32 v[22:23], v[22:23], v[236:237] op_sel_hi:[1,0]
	v_add_f32_e32 v34, 1.0, v42
	v_add_f32_e32 v35, 1.0, v43
	v_rcp_f32_e32 v34, v34
	v_mul_f32_e32 v36, 0xbfb8aa3b, v26
	v_mul_f32_e32 v37, 0xbfb8aa3b, v27
	v_rcp_f32_e32 v35, v35
	v_exp_f32_e32 v36, v36
	v_exp_f32_e32 v37, v37
	v_pk_mul_f32 v[18:19], v[18:19], v[236:237] op_sel_hi:[1,0]
	v_pk_mul_f32 v[30:31], v[30:31], v[34:35]
	v_add_f32_e32 v36, 1.0, v36
	v_add_f32_e32 v37, 1.0, v37
	v_pk_mul_f32 v[22:23], v[22:23], v[30:31]
	v_pk_mul_f32 v[30:31], v[32:33], v[236:237] op_sel_hi:[1,0]
	v_rcp_f32_e32 v36, v36
	v_rcp_f32_e32 v37, v37
	v_mul_f32_e32 v32, 0xbfb8aa3b, v30
	v_mul_f32_e32 v33, 0xbfb8aa3b, v31
	v_exp_f32_e32 v32, v32
	v_exp_f32_e32 v33, v33
	v_pk_mul_f32 v[26:27], v[26:27], v[36:37]
	v_pk_mul_f32 v[28:29], v[28:29], v[236:237] op_sel_hi:[1,0]
	v_pk_mul_f32 v[26:27], v[18:19], v[26:27]
	v_add_f32_e32 v18, 1.0, v32
	v_add_f32_e32 v19, 1.0, v33
	v_mul_f32_e32 v32, 0xbfb8aa3b, v28
	v_mul_f32_e32 v33, 0xbfb8aa3b, v29
	v_exp_f32_e32 v32, v32
	v_exp_f32_e32 v33, v33
	v_rcp_f32_e32 v18, v18
	v_rcp_f32_e32 v19, v19
	v_add_f32_e32 v32, 1.0, v32
	v_add_f32_e32 v33, 1.0, v33
	v_rcp_f32_e32 v32, v32
	v_rcp_f32_e32 v33, v33
	v_pk_mul_f32 v[18:19], v[30:31], v[18:19]
	v_pk_mul_f32 v[24:25], v[24:25], v[236:237] op_sel_hi:[1,0]
	v_pk_mul_f32 v[20:21], v[20:21], v[236:237] op_sel_hi:[1,0]
	v_pk_mul_f32 v[24:25], v[24:25], v[18:19]
	v_pk_mul_f32 v[18:19], v[28:29], v[32:33]
	v_add_u32_e32 v30, 0xa0, v118
	v_pk_mul_f32 v[28:29], v[20:21], v[18:19]
	v_cvt_pk_bf16_f32 v19, v24, v25
	v_mov_b32_e32 v24, v237
	v_pk_mul_f32 v[14:15], v[14:15], v[24:25] op_sel_hi:[1,0]
	v_cvt_pk_bf16_f32 v20, v26, v27
	v_mul_f32_e32 v25, 0xbfb8aa3b, v14
	v_mul_f32_e32 v26, 0xbfb8aa3b, v15
	v_exp_f32_e32 v25, v25
	v_exp_f32_e32 v26, v26
	v_cvt_pk_bf16_f32 v18, v22, v23
	v_mad_i64_i32 v[22:23], s[22:23], v30, s38, v[114:115]
	v_cvt_pk_bf16_f32 v21, v28, v29
	v_lshl_add_u64 v[22:23], v[22:23], 0, v[116:117]
	global_store_dwordx4 v[22:23], v[18:21], off
	v_pk_mul_f32 v[10:11], v[10:11], v[24:25] op_sel_hi:[1,0]
	v_pk_mul_f32 v[6:7], v[6:7], v[24:25] op_sel_hi:[1,0]
	v_add_f32_e32 v18, 1.0, v25
	v_add_f32_e32 v19, 1.0, v26
	v_rcp_f32_e32 v18, v18
	v_mul_f32_e32 v20, 0xbfb8aa3b, v10
	v_mul_f32_e32 v21, 0xbfb8aa3b, v11
	v_rcp_f32_e32 v19, v19
	v_exp_f32_e32 v20, v20
	v_exp_f32_e32 v21, v21
	v_pk_mul_f32 v[2:3], v[2:3], v[24:25] op_sel_hi:[1,0]
	v_pk_mul_f32 v[14:15], v[14:15], v[18:19]
	v_add_f32_e32 v20, 1.0, v20
	v_add_f32_e32 v21, 1.0, v21
	v_pk_mul_f32 v[6:7], v[6:7], v[14:15]
	v_pk_mul_f32 v[14:15], v[16:17], v[24:25] op_sel_hi:[1,0]
	v_rcp_f32_e32 v20, v20
	v_rcp_f32_e32 v21, v21
	v_mul_f32_e32 v16, 0xbfb8aa3b, v14
	v_mul_f32_e32 v17, 0xbfb8aa3b, v15
	v_exp_f32_e32 v16, v16
	v_exp_f32_e32 v17, v17
	v_pk_mul_f32 v[10:11], v[10:11], v[20:21]
	v_pk_mul_f32 v[12:13], v[12:13], v[24:25] op_sel_hi:[1,0]
	v_pk_mul_f32 v[10:11], v[2:3], v[10:11]
	v_add_f32_e32 v2, 1.0, v16
	v_add_f32_e32 v3, 1.0, v17
	v_mul_f32_e32 v16, 0xbfb8aa3b, v12
	v_mul_f32_e32 v17, 0xbfb8aa3b, v13
	v_exp_f32_e32 v16, v16
	v_exp_f32_e32 v17, v17
	v_rcp_f32_e32 v2, v2
	v_rcp_f32_e32 v3, v3
	v_add_f32_e32 v16, 1.0, v16
	v_add_f32_e32 v17, 1.0, v17
	v_rcp_f32_e32 v16, v16
	v_rcp_f32_e32 v17, v17
	v_pk_mul_f32 v[2:3], v[14:15], v[2:3]
	v_pk_mul_f32 v[8:9], v[8:9], v[24:25] op_sel_hi:[1,0]
	v_pk_mul_f32 v[4:5], v[4:5], v[24:25] op_sel_hi:[1,0]
	v_pk_mul_f32 v[8:9], v[8:9], v[2:3]
	v_pk_mul_f32 v[2:3], v[12:13], v[16:17]
	v_add_u32_e32 v14, 0xb0, v118
	v_pk_mul_f32 v[12:13], v[4:5], v[2:3]
	v_cvt_pk_bf16_f32 v2, v6, v7
	v_mad_i64_i32 v[6:7], s[22:23], v14, s38, v[114:115]
	v_cvt_pk_bf16_f32 v3, v8, v9
	v_cvt_pk_bf16_f32 v4, v10, v11
	v_cvt_pk_bf16_f32 v5, v12, v13
	v_lshl_add_u64 v[6:7], v[6:7], 0, v[116:117]
	s_mov_b64 s[0:1], -1
	global_store_dwordx4 v[6:7], v[2:5], off
	s_cbranch_vccnz .LBB0_1710
	s_andn2_b64 vcc, exec, s[4:5]
	s_cbranch_vccnz .LBB0_1709
	s_barrier
	s_branch .LBB0_1709
